# sliding-window items pulled from a device work queue (all blocks incl. compression-MLP blocks) instead of static striding; SLC selection words cached in registers
# speedup vs baseline: 1.0197x; 1.0095x over previous
; template <int ph>
; __device__ __forceinline__ void run_phase(LAS unsigned char* lds, int G, int bid, unsigned* bar_ctr, unsigned& nbar) {
;     ...
;             if (PHON(20)) {
;                 const int skip = G > 64 ? 32 : 0;
;                 if (bid >= skip) for (int it = bid - skip; it < 512; it += G - skip) nsa_item<M_WIN>(P, lds, it & 7, it >> 3);
.LBB0_2148:
	s_cmp_gt_i32 s44, 64
	s_cselect_b64 s[4:5], -1, 0
	s_and_b64 s[6:7], s[4:5], exec
	s_cselect_b32 s6, 32, 0
	s_cmp_ge_i32 s2, s6
	s_nop 0
	s_sub_i32 s33, s2, s6
	s_cmpk_gt_i32 s33, 0x1ff
	s_movk_i32 s45, 0x1ff
	s_nop 0
	s_load_dwordx2 s[38:39], s[48:49], 0x78
	s_load_dwordx2 s[50:51], s[48:49], 0xb8
	s_and_b64 s[4:5], s[4:5], exec
	s_cselect_b32 s59, 0xffffffe0, 0
	v_mbcnt_lo_u32_b32 v2, -1, 0
	s_mov_b32 s49, 0
	s_waitcnt lgkmcnt(0)
	s_add_u32 s52, s50, 0xf210000
	s_addc_u32 s53, s51, 0
	s_add_u32 s46, s50, 0x12a18000
	s_addc_u32 s47, s51, 0
	s_add_u32 s54, s50, 0x9210000
	s_addc_u32 s55, s51, 0
	s_add_u32 s56, s50, 0x1e510040
	v_and_b32_e32 v1, 0x3ff, v0
	s_addc_u32 s57, s51, 0
	s_add_i32 s59, s59, s44
	s_movk_i32 s76, 0x80
	s_mov_b32 s77, 0x800000
	s_mov_b32 s78, 0x3f317217
	s_mov_b32 s79, 0x7f800000
	s_mov_b32 s80, 0x40051592
	s_movk_i32 s81, 0x100
	v_mov_b32_e32 v3, 0
	s_movk_i32 s82, 0x200
	s_movk_i32 s83, 0x110
	s_movk_i32 s84, 0x90
	s_mov_b32 s58, 0x3e0293ee
	s_waitcnt vmcnt(0)
	v_mbcnt_hi_u32_b32 v184, -1, v2
	s_movk_i32 s85, 0x60
	v_mov_b32_e32 v185, 0x41b17218
	v_mov_b32_e32 v186, 0x100
	v_mov_b32_e32 v187, 0x80
	v_mov_b32_e32 v188, 0xf149f2ca
	s_branch .Lwinq_pop

; #define LAS __attribute__((address_space(3)))
; __device__ __forceinline__ int otid() { int t = threadIdx.x; asm volatile("" : "+v"(t)); return t; }
; __device__ __forceinline__ void st_bf4(bfraw* p, f32x4 v) { u32x2 o; o[0] = pack2(v[0], v[1]); o[1] = pack2(v[2], v[3]); *(u32x2*)p = o; }
; template <int MODE>
; __device__ __forceinline__ void nsa_item(CPR P, LAS unsigned char* lds, int h, int qb) {
;     ...
;     l += __shfl_xor(l, 32);
;     const float gate = gates[(size_t)t * 24 + (MODE == M_WIN ? 16 : 8) + h];
;     const float sc = gate / l;
;     const size_t ob = (size_t)t * 1024 + h * 128 + 4 * g;
;     u32x2 cq[16], wq[16];
;     if (MODE == M_SLC) {
; #pragma unroll
;         for (int i = 0; i < 16; ++i) { const size_t o = ob + (i >> 2) * 32 + (i & 3) * 8; cq[i] = *(const u32x2*)(ocmp + o); wq[i] = *(const u32x2*)(owin + o); }
;     }
; #pragma unroll
;     for (int db = 0; db < 4; ++db)
; #pragma unroll
;         for (int r4 = 0; r4 < 4; ++r4) {
;             f32x4 v; v[0] = O[db][r4 * 4] * sc; v[1] = O[db][r4 * 4 + 1] * sc; v[2] = O[db][r4 * 4 + 2] * sc; v[3] = O[db][r4 * 4 + 3] * sc;
;             const size_t o = ob + db * 32 + r4 * 8;
;             if (MODE == M_WIN) st_bf4(owin + o, v);
; __device__ __forceinline__ int queue_pop(unsigned* qctr, LAS unsigned char* lds) {
;     LAS int* slot = (LAS int*)(lds + LDS_BYTES - 64);
;     __syncthreads();
;     if (otid() == 0) slot[0] = (int)__hip_atomic_fetch_add(qctr, 1u, __ATOMIC_RELAXED, __HIP_MEMORY_SCOPE_AGENT);
;     __syncthreads();
;     return __builtin_amdgcn_readfirstlane(slot[0]);
; }
.LBB0_2152:
	v_mov_b64_e32 v[4:5], s[56:57]
	v_mad_i64_i32 v[4:5], s[4:5], v164, s85, v[4:5]
	v_lshl_add_u64 v[4:5], v[162:163], 2, v[4:5]
	global_load_dword v6, v[4:5], off
	v_and_b32_e32 v7, 64, v184
	v_xor_b32_e32 v2, 32, v184
	v_add_u32_e32 v7, 64, v7
	v_cmp_lt_i32_e32 vcc, v2, v7
	v_lshlrev_b64 v[4:5], 11, v[164:165]
	s_lshl_b32 s48, s48, 8
	v_cndmask_b32_e32 v2, v184, v2, vcc
	v_lshlrev_b32_e32 v2, 2, v2
	ds_bpermute_b32 v7, v2, v206
	v_lshl_add_u64 v[4:5], s[54:55], 0, v[4:5]
	v_lshlrev_b32_e32 v2, 3, v189
	v_lshl_add_u64 v[4:5], v[4:5], 0, s[48:49]
	v_lshl_add_u64 v[4:5], v[4:5], 0, v[2:3]
	s_waitcnt lgkmcnt(0)
	v_add_f32_e32 v7, v206, v7
	s_nop 0
	s_nop 0
	s_waitcnt vmcnt(0)
	v_div_scale_f32 v8, s[4:5], v7, v7, v6
	v_rcp_f32_e32 v9, v8
	v_div_scale_f32 v2, vcc, v6, v7, v6
	v_fma_f32 v10, -v8, v9, 1.0
	v_fmac_f32_e32 v9, v10, v9
	v_mul_f32_e32 v10, v2, v9
	v_fma_f32 v11, -v8, v10, v2
	v_fmac_f32_e32 v10, v11, v9
	v_fma_f32 v2, -v8, v10, v2
	v_div_fmas_f32 v2, v2, v9, v10
	v_div_fixup_f32 v2, v2, v7, v6
	v_mul_f32_e32 v6, v66, v2
	v_mul_f32_e32 v7, v67, v2
	v_mul_f32_e32 v8, v68, v2
	v_mul_f32_e32 v9, v69, v2
	v_cvt_pk_bf16_f32 v6, v6, v7
	v_cvt_pk_bf16_f32 v7, v8, v9
	v_mul_f32_e32 v10, v70, v2
	v_mul_f32_e32 v11, v71, v2
	v_mul_f32_e32 v12, v72, v2
	v_mul_f32_e32 v13, v73, v2
	global_store_dwordx2 v[4:5], v[6:7], off
	v_cvt_pk_bf16_f32 v6, v10, v11
	v_cvt_pk_bf16_f32 v7, v12, v13
	v_mul_f32_e32 v14, v74, v2
	v_mul_f32_e32 v15, v75, v2
	v_mul_f32_e32 v16, v76, v2
	v_mul_f32_e32 v17, v77, v2
	global_store_dwordx2 v[4:5], v[6:7], off offset:16
	v_cvt_pk_bf16_f32 v6, v14, v15
	v_cvt_pk_bf16_f32 v7, v16, v17
	v_mul_f32_e32 v66, v78, v2
	v_mul_f32_e32 v67, v79, v2
	v_mul_f32_e32 v68, v80, v2
	v_mul_f32_e32 v69, v81, v2
	global_store_dwordx2 v[4:5], v[6:7], off offset:32
	v_cvt_pk_bf16_f32 v6, v66, v67
	v_cvt_pk_bf16_f32 v7, v68, v69
	v_mul_f32_e32 v50, v50, v2
	v_mul_f32_e32 v51, v51, v2
	v_mul_f32_e32 v52, v52, v2
	v_mul_f32_e32 v53, v53, v2
	global_store_dwordx2 v[4:5], v[6:7], off offset:48
	v_cvt_pk_bf16_f32 v6, v50, v51
	v_cvt_pk_bf16_f32 v7, v52, v53
	v_mul_f32_e32 v54, v54, v2
	v_mul_f32_e32 v55, v55, v2
	v_mul_f32_e32 v56, v56, v2
	v_mul_f32_e32 v57, v57, v2
	global_store_dwordx2 v[4:5], v[6:7], off offset:64
	v_cvt_pk_bf16_f32 v6, v54, v55
	v_cvt_pk_bf16_f32 v7, v56, v57
	v_mul_f32_e32 v58, v58, v2
	v_mul_f32_e32 v59, v59, v2
	v_mul_f32_e32 v60, v60, v2
	v_mul_f32_e32 v61, v61, v2
	global_store_dwordx2 v[4:5], v[6:7], off offset:80
	v_cvt_pk_bf16_f32 v6, v58, v59
	v_cvt_pk_bf16_f32 v7, v60, v61
	v_mul_f32_e32 v62, v62, v2
	v_mul_f32_e32 v63, v63, v2
	v_mul_f32_e32 v64, v64, v2
	v_mul_f32_e32 v65, v65, v2
	global_store_dwordx2 v[4:5], v[6:7], off offset:96
	v_cvt_pk_bf16_f32 v6, v62, v63
	v_cvt_pk_bf16_f32 v7, v64, v65
	v_mul_f32_e32 v34, v34, v2
	v_mul_f32_e32 v35, v35, v2
	v_mul_f32_e32 v36, v36, v2
	v_mul_f32_e32 v37, v37, v2
	global_store_dwordx2 v[4:5], v[6:7], off offset:112
	v_cvt_pk_bf16_f32 v6, v34, v35
	v_cvt_pk_bf16_f32 v7, v36, v37
	v_mul_f32_e32 v38, v38, v2
	v_mul_f32_e32 v39, v39, v2
	v_mul_f32_e32 v40, v40, v2
	v_mul_f32_e32 v41, v41, v2
	global_store_dwordx2 v[4:5], v[6:7], off offset:128
	v_cvt_pk_bf16_f32 v6, v38, v39
	v_cvt_pk_bf16_f32 v7, v40, v41
	v_mul_f32_e32 v42, v42, v2
	v_mul_f32_e32 v43, v43, v2
	v_mul_f32_e32 v44, v44, v2
	v_mul_f32_e32 v45, v45, v2
	global_store_dwordx2 v[4:5], v[6:7], off offset:144
	v_cvt_pk_bf16_f32 v6, v42, v43
	v_cvt_pk_bf16_f32 v7, v44, v45
	global_store_dwordx2 v[4:5], v[6:7], off offset:160
	v_mul_f32_e32 v6, v46, v2
	v_mul_f32_e32 v7, v47, v2
	v_mul_f32_e32 v8, v48, v2
	v_mul_f32_e32 v9, v49, v2
	v_cvt_pk_bf16_f32 v6, v6, v7
	v_cvt_pk_bf16_f32 v7, v8, v9
	global_store_dwordx2 v[4:5], v[6:7], off offset:176
	v_mul_f32_e32 v6, v18, v2
	v_mul_f32_e32 v7, v19, v2
	v_mul_f32_e32 v8, v20, v2
	v_mul_f32_e32 v9, v21, v2
	v_cvt_pk_bf16_f32 v6, v6, v7
	v_cvt_pk_bf16_f32 v7, v8, v9
	global_store_dwordx2 v[4:5], v[6:7], off offset:192
	v_mul_f32_e32 v6, v22, v2
	v_mul_f32_e32 v7, v23, v2
	v_mul_f32_e32 v8, v24, v2
	v_mul_f32_e32 v9, v25, v2
	v_cvt_pk_bf16_f32 v6, v6, v7
	v_cvt_pk_bf16_f32 v7, v8, v9
	global_store_dwordx2 v[4:5], v[6:7], off offset:208
	v_mul_f32_e32 v6, v26, v2
	v_mul_f32_e32 v7, v27, v2
	v_mul_f32_e32 v8, v28, v2
	v_mul_f32_e32 v9, v29, v2
	v_cvt_pk_bf16_f32 v6, v6, v7
	v_cvt_pk_bf16_f32 v7, v8, v9
	global_store_dwordx2 v[4:5], v[6:7], off offset:224
	v_mul_f32_e32 v6, v30, v2
	v_mul_f32_e32 v7, v31, v2
	v_mul_f32_e32 v8, v32, v2
	v_mul_f32_e32 v2, v33, v2
	v_cvt_pk_bf16_f32 v6, v6, v7
	v_cvt_pk_bf16_f32 v7, v8, v2
	global_store_dwordx2 v[4:5], v[6:7], off offset:240
	s_branch .Lwinq_pop
.Lwinq_pop:
	s_barrier
	v_cmp_eq_u32_e32 vcc, 0, v1
	s_and_saveexec_b64 s[4:5], vcc
	s_cbranch_execz .Lwinq_1
	v_mov_b32_e32 v8, 0
	v_mov_b32_e32 v9, 1
	global_atomic_add v9, v8, v9, s[92:93] offset:1568 sc0
	v_mov_b32_e32 v10, 0x240c0
	s_waitcnt vmcnt(0)
	ds_write_b32 v10, v9
.Lwinq_1:
	s_or_b64 exec, exec, s[4:5]
	s_waitcnt lgkmcnt(0)
	s_barrier
	v_mov_b32_e32 v10, 0x240c0
	ds_read_b32 v10, v10
	s_waitcnt lgkmcnt(0)
	v_readfirstlane_b32 s33, v10
	s_cmpk_lt_i32 s33, 0x200
	s_cbranch_scc0 .LBB0_2242
